# barrier: dropped the per-XCD generation increment (unused now that all workgroups poll the cross-XCD generation); attention staging edits kept
# baseline (speedup 1.0000x reference)
.LBB0_161:
	s_or_b64 exec, exec, s[26:27]
	s_mov_b64 s[26:27], exec
	v_mbcnt_lo_u32_b32 v0, s26, 0
	v_mbcnt_hi_u32_b32 v0, s27, v0
	v_cmp_eq_u32_e32 vcc, 0, v0
	s_waitcnt vmcnt(0)
	buffer_inv sc1
	s_and_saveexec_b64 s[28:29], vcc
	s_cbranch_execz .LBB0_163
	s_bcnt1_i32_b64 s0, s[26:27]
	v_readlane_b32 s14, v251, 48
	v_mov_b32_e32 v0, s0
	v_readlane_b32 s15, v251, 49
	s_nop 4
	s_nop 0

.LBB0_995:
	s_bcnt1_i32_b64 s0, s[26:27]
	v_readlane_b32 s14, v251, 48
	v_mov_b32_e32 v0, s0
	v_readlane_b32 s15, v251, 49
	s_nop 4
	s_nop 0
	s_getpc_b64 s[98:99]
